# phase 1 adaLN reduce: all 9 loads of an element issued before the first wait
# speedup vs baseline: 1.0018x; 1.0018x over previous
.LBB0_111:
	v_add_co_u32_e32 v4, vcc, s16, v0
	v_mul_hi_i32 v15, v2, s14
	s_nop 0
	v_addc_co_u32_e32 v5, vcc, -1, v1, vcc
	v_add_co_u32_e32 v6, vcc, s17, v0
	v_lshrrev_b32_e32 v17, 31, v15
	s_nop 0
	v_addc_co_u32_e32 v7, vcc, -1, v1, vcc
	v_add_co_u32_e32 v8, vcc, s18, v0
	v_ashrrev_i32_e32 v18, 11, v15
	s_nop 0
	v_addc_co_u32_e32 v9, vcc, -1, v1, vcc
	v_add_co_u32_e32 v10, vcc, s19, v0
	v_mul_hi_i32 v3, v2, s7
	s_nop 0
	v_addc_co_u32_e32 v11, vcc, -1, v1, vcc
	v_add_co_u32_e32 v12, vcc, s20, v0
	v_lshrrev_b32_e32 v16, 31, v3
	s_nop 0
	v_addc_co_u32_e32 v13, vcc, -1, v1, vcc
	global_load_dword v19, v[4:5], off
	global_load_dword v20, v[6:7], off
	global_load_dword v21, v[8:9], off
	global_load_dword v22, v[10:11], off
	global_load_dword v23, v[12:13], off
	v_add_u32_e32 v4, v18, v17
	v_ashrrev_i32_e32 v3, 13, v3
	v_mul_i32_i24_e32 v4, 0x3000, v4
	v_add_u32_e32 v3, v3, v16
	v_sub_u32_e32 v4, v2, v4
	v_mad_i32_i24 v4, v3, s15, v4
	v_ashrrev_i32_e32 v5, 31, v4
	s_waitcnt lgkmcnt(0)
	v_lshl_add_u64 v[4:5], v[4:5], 2, s[8:9]
	global_load_dword v3, v[4:5], off
	v_add_co_u32_e32 v14, vcc, s21, v0
	v_add_u32_e32 v2, s6, v2
	s_nop 0
	v_addc_co_u32_e32 v15, vcc, -1, v1, vcc
	v_add_co_u32_e32 v4, vcc, s22, v0
	s_nop 1
	v_addc_co_u32_e32 v5, vcc, -1, v1, vcc
	global_load_dword v6, v[14:15], off
	global_load_dword v7, v[4:5], off
	global_load_dword v8, v[0:1], off
	s_waitcnt vmcnt(3)
	v_add_f32_e32 v3, v3, v19
	v_add_f32_e32 v3, v3, v20
	v_add_f32_e32 v3, v3, v21
	v_add_f32_e32 v3, v3, v22
	v_add_co_u32_e32 v4, vcc, 0xffb10000, v0
	v_add_f32_e32 v3, v3, v23
	s_nop 0
	v_addc_co_u32_e32 v5, vcc, -1, v1, vcc
	v_cmp_lt_i32_e32 vcc, s23, v2
	v_lshl_add_u64 v[0:1], v[0:1], 0, s[10:11]
	s_or_b64 s[12:13], vcc, s[12:13]
	s_waitcnt vmcnt(2)
	v_add_f32_e32 v3, v3, v6
	s_waitcnt vmcnt(1)
	v_add_f32_e32 v3, v3, v7
	s_waitcnt vmcnt(0)
	v_add_f32_e32 v3, v3, v8
	global_store_dword v[4:5], v3, off
	s_andn2_b64 exec, exec, s[12:13]
	s_cbranch_execnz .LBB0_111

.LBB0_1468:
	s_cmp_eq_u32 s26, 1
	s_cselect_b32 s8, 0x2000, s91
	s_cselect_b32 s9, 0x4000, s83
	s_cmp_eq_u32 s26, 0
	s_cselect_b32 s8, 0, s8
	s_cselect_b32 s29, 0x2000, s9
	s_add_i32 s52, s22, s8
	s_cmp_ge_i32 s52, s29
	s_cbranch_scc1 .LBB0_1467
	s_mul_i32 s88, s26, 0x3000
	s_lshl_b64 s[8:9], s[88:89], 2
	s_add_u32 s12, s24, s8
	s_addc_u32 s13, s25, s9
	s_add_u32 s8, s12, 0x6000
	s_addc_u32 s9, s13, 0
	s_add_u32 s12, s12, 0x8000
	v_lshlrev_b32_e32 v122, 2, v108
	s_addc_u32 s13, s13, 0
	global_load_dwordx4 v[28:31], v122, s[8:9]
	global_load_dwordx4 v[32:35], v122, s[8:9] offset:16
	global_load_dwordx4 v[36:39], v[116:117], off
	global_load_dwordx4 v[40:43], v[116:117], off offset:16
	global_load_dwordx4 v[44:47], v122, s[12:13]
	global_load_dwordx4 v[48:51], v122, s[12:13] offset:16
	v_lshlrev_b32_e32 v132, 2, v104
	v_lshlrev_b32_e32 v2, 2, v0
	s_ashr_i32 s53, s52, 31
	s_waitcnt vmcnt(0)
	v_pk_add_f32 v[50:51], v[50:51], 1.0 op_sel_hi:[1,0]
	v_pk_add_f32 v[48:49], v[48:49], 1.0 op_sel_hi:[1,0]
	v_pk_mul_f32 v[124:125], v[42:43], v[50:51]
	v_pk_mul_f32 v[126:127], v[40:41], v[48:49]
	v_pk_add_f32 v[40:41], v[46:47], 1.0 op_sel_hi:[1,0]
	v_pk_add_f32 v[42:43], v[44:45], 1.0 op_sel_hi:[1,0]
	v_pk_mul_f32 v[128:129], v[38:39], v[40:41]
	v_pk_mul_f32 v[130:131], v[36:37], v[42:43]
	global_load_dwordx4 v[36:39], v132, s[8:9]
	global_load_dwordx4 v[40:43], v132, s[8:9] offset:16
	global_load_dwordx4 v[44:47], v[114:115], off
	global_load_dwordx4 v[48:51], v[114:115], off offset:16
	global_load_dwordx4 v[52:55], v132, s[12:13]
	global_load_dwordx4 v[56:59], v132, s[12:13] offset:16
	s_waitcnt vmcnt(0)
	v_pk_add_f32 v[58:59], v[58:59], 1.0 op_sel_hi:[1,0]
	v_pk_add_f32 v[56:57], v[56:57], 1.0 op_sel_hi:[1,0]
	v_pk_mul_f32 v[134:135], v[50:51], v[58:59]
	v_pk_mul_f32 v[136:137], v[48:49], v[56:57]
	v_pk_add_f32 v[48:49], v[54:55], 1.0 op_sel_hi:[1,0]
	v_pk_add_f32 v[50:51], v[52:53], 1.0 op_sel_hi:[1,0]
	v_pk_mul_f32 v[138:139], v[46:47], v[48:49]
	v_pk_mul_f32 v[140:141], v[44:45], v[50:51]
	global_load_dwordx4 v[44:47], v189, s[8:9]
	global_load_dwordx4 v[48:51], v189, s[8:9] offset:16
	global_load_dwordx4 v[52:55], v[112:113], off offset:2048
	global_load_dwordx4 v[56:59], v[112:113], off offset:2064
	global_load_dwordx4 v[60:63], v189, s[12:13]
	global_load_dwordx4 v[64:67], v189, s[12:13] offset:16
	s_waitcnt vmcnt(0)
	v_pk_add_f32 v[66:67], v[66:67], 1.0 op_sel_hi:[1,0]
	v_pk_add_f32 v[64:65], v[64:65], 1.0 op_sel_hi:[1,0]
	v_pk_mul_f32 v[142:143], v[58:59], v[66:67]
	v_pk_mul_f32 v[144:145], v[56:57], v[64:65]
	v_pk_add_f32 v[56:57], v[62:63], 1.0 op_sel_hi:[1,0]
	v_pk_add_f32 v[58:59], v[60:61], 1.0 op_sel_hi:[1,0]
	v_pk_mul_f32 v[146:147], v[54:55], v[56:57]
	v_pk_mul_f32 v[148:149], v[52:53], v[58:59]
	global_load_dwordx4 v[52:55], v2, s[8:9]
	global_load_dwordx4 v[56:59], v2, s[8:9] offset:16
	global_load_dwordx4 v[60:63], v[112:113], off
	global_load_dwordx4 v[64:67], v[112:113], off offset:16
	global_load_dwordx4 v[68:71], v2, s[12:13]
	global_load_dwordx4 v[72:75], v2, s[12:13] offset:16
	s_lshl_b64 s[8:9], s[52:53], 12
	v_lshl_add_u64 v[158:159], v[120:121], 0, s[8:9]
	s_waitcnt vmcnt(0)
	v_pk_add_f32 v[74:75], v[74:75], 1.0 op_sel_hi:[1,0]
	v_pk_add_f32 v[72:73], v[72:73], 1.0 op_sel_hi:[1,0]
	v_pk_mul_f32 v[150:151], v[66:67], v[74:75]
	v_pk_mul_f32 v[152:153], v[64:65], v[72:73]
	v_pk_add_f32 v[64:65], v[70:71], 1.0 op_sel_hi:[1,0]
	v_pk_add_f32 v[66:67], v[68:69], 1.0 op_sel_hi:[1,0]
	v_pk_mul_f32 v[154:155], v[62:63], v[64:65]
	v_pk_mul_f32 v[156:157], v[60:61], v[66:67]
	s_branch .LBB0_1471
